# attention far tiles: QK in two key halves, exp of the first half issued under the second half's MFMAs (far decision taken before QK; rescale falls back to the old path)
# baseline (speedup 1.0000x reference)
.Lat_nodma:
	s_add_i32 s23, s18, s20
	s_add_i32 s10, s20, 63
	s_add_i32 s8, s23, 0xffffe0bf
	s_cmpk_lt_i32 s8, 0xffa6
	s_cselect_b64 s[8:9], -1, 0
	s_cmp_lt_i32 s10, s15
	s_cselect_b64 s[12:13], -1, 0
	s_and_b64 s[10:11], s[12:13], s[8:9]
	s_and_b64 vcc, exec, s[10:11]
	s_cbranch_vccnz .Lat_farqk
	s_and_b32 s22, s21, 0x8000
	s_add_i32 s8, s43, s22
	v_add_u32_e32 v192, s8, v246
	ds_read_b128 v[4:7], v192
	ds_read_b128 v[8:11], v192 offset:8192
	v_xor_b32_e32 v193, 32, v192
	ds_read_b128 v[12:15], v193
	ds_read_b128 v[178:181], v193 offset:8192
	v_xor_b32_e32 v194, 64, v192
	ds_read_b128 v[182:185], v194
	ds_read_b128 v[186:189], v194 offset:8192
	v_xor_b32_e32 v195, 0x60, v192
	s_waitcnt lgkmcnt(0)
	v_mfma_f32_32x32x16_bf16 v[162:177], v[4:7], v[210:213], 0
	v_mfma_f32_32x32x16_bf16 v[146:161], v[8:11], v[210:213], 0
	ds_read_b128 v[4:7], v195
	ds_read_b128 v[8:11], v195 offset:8192
	v_mfma_f32_32x32x16_bf16 v[162:177], v[12:15], v[214:217], v[162:177]
	v_mfma_f32_32x32x16_bf16 v[146:161], v[178:181], v[214:217], v[146:161]
	ds_read_b128 v[12:15], v192 offset:128
	ds_read_b128 v[178:181], v192 offset:8320
	v_mfma_f32_32x32x16_bf16 v[162:177], v[182:185], v[218:221], v[162:177]
	v_mfma_f32_32x32x16_bf16 v[146:161], v[186:189], v[218:221], v[146:161]
	ds_read_b128 v[182:185], v193 offset:128
	ds_read_b128 v[186:189], v193 offset:8320
	s_waitcnt lgkmcnt(0)
	v_mfma_f32_32x32x16_bf16 v[162:177], v[4:7], v[222:225], v[162:177]
	v_mfma_f32_32x32x16_bf16 v[146:161], v[8:11], v[222:225], v[146:161]
	ds_read_b128 v[4:7], v194 offset:128
	ds_read_b128 v[8:11], v194 offset:8320
	v_mfma_f32_32x32x16_bf16 v[162:177], v[12:15], v[226:229], v[162:177]
	v_mfma_f32_32x32x16_bf16 v[146:161], v[178:181], v[226:229], v[146:161]
	ds_read_b128 v[12:15], v195 offset:128
	ds_read_b128 v[178:181], v195 offset:8320
	v_mfma_f32_32x32x16_bf16 v[162:177], v[182:185], v[230:233], v[162:177]
	v_mfma_f32_32x32x16_bf16 v[146:161], v[186:189], v[230:233], v[146:161]
	s_waitcnt lgkmcnt(0)
	v_mfma_f32_32x32x16_bf16 v[162:177], v[4:7], v[234:237], v[162:177]
	v_mfma_f32_32x32x16_bf16 v[146:161], v[8:11], v[234:237], v[146:161]
	v_mfma_f32_32x32x16_bf16 v[162:177], v[12:15], v[238:241], v[162:177]
	v_mfma_f32_32x32x16_bf16 v[146:161], v[178:181], v[238:241], v[146:161]
	s_add_i32 s23, s18, s20
	s_add_i32 s10, s20, 63
	s_add_i32 s8, s23, 0xffffe0bf
	s_cmpk_lt_i32 s8, 0xffa6
	s_cselect_b64 s[8:9], -1, 0
	s_cmp_lt_i32 s10, s15
	s_cselect_b64 s[12:13], -1, 0
	s_and_b64 s[10:11], s[12:13], s[8:9]
	s_and_b64 vcc, exec, s[10:11]
	s_cbranch_vccnz .Lat_farmax
	v_lshrrev_b32_e32 v11, 3, v242
	v_and_b32_e32 v11, 4, v11
	v_and_b32_e32 v2, 31, v242
	v_sub_u32_e32 v2, v11, v2
	v_add_u32_e32 v2, s23, v2
	s_add_i32 s23, 0, 0x18600
	v_lshl_add_u32 v2, v2, 2, s23
	ds_read2_b32 v[178:179], v2 offset0:0 offset1:1
	ds_read2_b32 v[180:181], v2 offset0:2 offset1:3
	ds_read2_b32 v[182:183], v2 offset0:8 offset1:9
	ds_read2_b32 v[184:185], v2 offset0:10 offset1:11
	ds_read2_b32 v[186:187], v2 offset0:16 offset1:17
	ds_read2_b32 v[188:189], v2 offset0:18 offset1:19
	ds_read2_b32 v[190:191], v2 offset0:24 offset1:25
	ds_read2_b32 v[192:193], v2 offset0:26 offset1:27
	ds_read2_b32 v[194:195], v2 offset0:32 offset1:33
	ds_read2_b32 v[196:197], v2 offset0:34 offset1:35
	ds_read2_b32 v[198:199], v2 offset0:40 offset1:41
	ds_read2_b32 v[200:201], v2 offset0:42 offset1:43
	ds_read2_b32 v[202:203], v2 offset0:48 offset1:49
	ds_read2_b32 v[204:205], v2 offset0:50 offset1:51
	ds_read2_b32 v[206:207], v2 offset0:56 offset1:57
	ds_read2_b32 v[208:209], v2 offset0:58 offset1:59
	s_waitcnt lgkmcnt(0)
	v_fmamk_f32 v162, v162, 0x3e0293ee, v178
	v_fmamk_f32 v146, v146, 0x3e0293ee, v194
	v_fmamk_f32 v163, v163, 0x3e0293ee, v179
	v_fmamk_f32 v147, v147, 0x3e0293ee, v195
	v_max_f32_e32 v2, v162, v146
	v_fmamk_f32 v164, v164, 0x3e0293ee, v180
	v_fmamk_f32 v148, v148, 0x3e0293ee, v196
	v_max3_f32 v2, v2, v163, v147
	v_fmamk_f32 v165, v165, 0x3e0293ee, v181
	v_fmamk_f32 v149, v149, 0x3e0293ee, v197
	v_max3_f32 v2, v2, v164, v148
	v_fmamk_f32 v166, v166, 0x3e0293ee, v182
	v_fmamk_f32 v150, v150, 0x3e0293ee, v198
	v_max3_f32 v2, v2, v165, v149
	v_fmamk_f32 v167, v167, 0x3e0293ee, v183
	v_fmamk_f32 v151, v151, 0x3e0293ee, v199
	v_max3_f32 v2, v2, v166, v150
	v_fmamk_f32 v168, v168, 0x3e0293ee, v184
	v_fmamk_f32 v152, v152, 0x3e0293ee, v200
	v_max3_f32 v2, v2, v167, v151
	v_fmamk_f32 v169, v169, 0x3e0293ee, v185
	v_fmamk_f32 v153, v153, 0x3e0293ee, v201
	v_max3_f32 v2, v2, v168, v152
	v_fmamk_f32 v170, v170, 0x3e0293ee, v186
	v_fmamk_f32 v154, v154, 0x3e0293ee, v202
	v_max3_f32 v2, v2, v169, v153
	v_fmamk_f32 v171, v171, 0x3e0293ee, v187
	v_fmamk_f32 v155, v155, 0x3e0293ee, v203
	v_max3_f32 v2, v2, v170, v154
	v_fmamk_f32 v172, v172, 0x3e0293ee, v188
	v_fmamk_f32 v156, v156, 0x3e0293ee, v204
	v_max3_f32 v2, v2, v171, v155
	v_fmamk_f32 v173, v173, 0x3e0293ee, v189
	v_fmamk_f32 v157, v157, 0x3e0293ee, v205
	v_max3_f32 v2, v2, v172, v156
	v_fmamk_f32 v174, v174, 0x3e0293ee, v190
	v_fmamk_f32 v158, v158, 0x3e0293ee, v206
	v_max3_f32 v2, v2, v173, v157
	v_fmamk_f32 v175, v175, 0x3e0293ee, v191
	v_fmamk_f32 v159, v159, 0x3e0293ee, v207
	v_max3_f32 v2, v2, v174, v158
	v_fmamk_f32 v176, v176, 0x3e0293ee, v192
	v_fmamk_f32 v160, v160, 0x3e0293ee, v208
	v_max3_f32 v2, v2, v175, v159
	v_fmamk_f32 v177, v177, 0x3e0293ee, v193
	v_fmamk_f32 v161, v161, 0x3e0293ee, v209
	v_max3_f32 v2, v2, v176, v160
	v_max3_f32 v4, v2, v177, v161
	s_branch .LBB0_2770

.Lat_rescale:
	v_lshrrev_b32_e32 v11, 3, v242
	v_and_b32_e32 v11, 4, v11
	v_and_b32_e32 v13, 64, v249
	v_max_f32_e32 v4, v4, v4
	v_max_f32_e32 v5, v251, v251
	v_max_f32_e32 v180, v5, v4
	v_sub_f32_e32 v4, v251, v180
	v_add_u32_e32 v12, 11, v11
	v_add_u32_e32 v14, 17, v11
	v_exp_f32_e32 v181, v4
	v_and_or_b32 v12, v12, 63, v13
	v_and_or_b32 v14, v14, 61, v13
	v_and_or_b32 v4, v11, 60, v13
	v_add_u32_e32 v8, 8, v11
	v_add_u32_e32 v9, 9, v11
	v_add_u32_e32 v10, 10, v11
	v_lshlrev_b32_e32 v182, 2, v12
	v_add_u32_e32 v12, 16, v11
	v_lshlrev_b32_e32 v183, 2, v14
	v_add_u32_e32 v14, 18, v11
	v_add_u32_e32 v15, 19, v11
	v_add_u32_e32 v16, 24, v11
	v_add_u32_e32 v17, 25, v11
	v_add_u32_e32 v178, 26, v11
	v_add_u32_e32 v11, 27, v11
	v_and_or_b32 v8, v8, 60, v13
	v_and_or_b32 v9, v9, 61, v13
	v_and_or_b32 v10, v10, 62, v13
	v_and_or_b32 v12, v12, 60, v13
	v_and_or_b32 v14, v14, 62, v13
	v_and_or_b32 v15, v15, 63, v13
	v_and_or_b32 v16, v16, 60, v13
	v_and_or_b32 v17, v17, 61, v13
	v_and_or_b32 v178, v178, 62, v13
	v_and_or_b32 v11, v11, 63, v13
	v_lshlrev_b32_e32 v7, 2, v4
	v_lshlrev_b32_e32 v8, 2, v8
	v_lshlrev_b32_e32 v9, 2, v9
	v_lshlrev_b32_e32 v10, 2, v10
	v_lshlrev_b32_e32 v12, 2, v12
	v_lshlrev_b32_e32 v14, 2, v14
	v_lshlrev_b32_e32 v15, 2, v15
	v_lshlrev_b32_e32 v16, 2, v16
	v_lshlrev_b32_e32 v17, 2, v17
	v_lshlrev_b32_e32 v178, 2, v178
	v_lshlrev_b32_e32 v11, 2, v11
	ds_bpermute_b32 v4, v7, v181
	ds_bpermute_b32 v5, v7, v181 offset:4
	ds_bpermute_b32 v6, v7, v181 offset:8
	ds_bpermute_b32 v7, v7, v181 offset:12
	ds_bpermute_b32 v8, v8, v181
	ds_bpermute_b32 v9, v9, v181
	ds_bpermute_b32 v10, v10, v181
	ds_bpermute_b32 v12, v12, v181
	ds_bpermute_b32 v14, v14, v181
	ds_bpermute_b32 v16, v16, v181
	ds_bpermute_b32 v178, v178, v181
	ds_bpermute_b32 v179, v11, v181
	ds_bpermute_b32 v17, v17, v181
	ds_bpermute_b32 v15, v15, v181
	ds_bpermute_b32 v13, v183, v181
	ds_bpermute_b32 v11, v182, v181
	s_waitcnt lgkmcnt(0)
	v_pk_mul_f32 v[128:129], v[128:129], v[178:179]
	v_pk_mul_f32 v[126:127], v[126:127], v[16:17]
	v_pk_mul_f32 v[124:125], v[124:125], v[14:15]
	v_pk_mul_f32 v[122:123], v[122:123], v[12:13]
	v_pk_mul_f32 v[120:121], v[120:121], v[10:11]
	v_pk_mul_f32 v[118:119], v[118:119], v[8:9]
	v_pk_mul_f32 v[116:117], v[116:117], v[6:7]
	v_pk_mul_f32 v[114:115], v[114:115], v[4:5]
	v_pk_mul_f32 v[112:113], v[112:113], v[178:179]
	v_pk_mul_f32 v[110:111], v[110:111], v[16:17]
	v_pk_mul_f32 v[108:109], v[108:109], v[14:15]
	v_pk_mul_f32 v[106:107], v[106:107], v[12:13]
	v_pk_mul_f32 v[104:105], v[104:105], v[10:11]
	v_pk_mul_f32 v[102:103], v[102:103], v[8:9]
	v_pk_mul_f32 v[100:101], v[100:101], v[6:7]
	v_pk_mul_f32 v[98:99], v[98:99], v[4:5]
	v_pk_mul_f32 v[144:145], v[144:145], v[178:179]
	v_pk_mul_f32 v[142:143], v[142:143], v[16:17]
	v_pk_mul_f32 v[140:141], v[140:141], v[14:15]
	v_pk_mul_f32 v[138:139], v[138:139], v[12:13]
	v_pk_mul_f32 v[136:137], v[136:137], v[10:11]
	v_pk_mul_f32 v[134:135], v[134:135], v[8:9]
	v_pk_mul_f32 v[132:133], v[132:133], v[6:7]
	v_pk_mul_f32 v[130:131], v[130:131], v[4:5]
	v_pk_mul_f32 v[96:97], v[96:97], v[178:179]
	v_pk_mul_f32 v[94:95], v[94:95], v[16:17]
	v_pk_mul_f32 v[92:93], v[92:93], v[14:15]
	v_pk_mul_f32 v[90:91], v[90:91], v[12:13]
	v_pk_mul_f32 v[88:89], v[88:89], v[10:11]
	v_pk_mul_f32 v[86:87], v[86:87], v[8:9]
	v_pk_mul_f32 v[84:85], v[84:85], v[6:7]
	v_pk_mul_f32 v[82:83], v[82:83], v[4:5]
	v_pk_mul_f32 v[80:81], v[80:81], v[178:179]
	v_pk_mul_f32 v[78:79], v[78:79], v[16:17]
	v_pk_mul_f32 v[76:77], v[76:77], v[14:15]
	v_pk_mul_f32 v[74:75], v[74:75], v[12:13]
	v_pk_mul_f32 v[72:73], v[72:73], v[10:11]
	v_pk_mul_f32 v[70:71], v[70:71], v[8:9]
	v_pk_mul_f32 v[68:69], v[68:69], v[6:7]
	v_pk_mul_f32 v[66:67], v[66:67], v[4:5]
	v_pk_mul_f32 v[64:65], v[64:65], v[178:179]
	v_pk_mul_f32 v[62:63], v[62:63], v[16:17]
	v_pk_mul_f32 v[60:61], v[60:61], v[14:15]
	v_pk_mul_f32 v[58:59], v[58:59], v[12:13]
	v_pk_mul_f32 v[56:57], v[56:57], v[10:11]
	v_pk_mul_f32 v[54:55], v[54:55], v[8:9]
	v_pk_mul_f32 v[52:53], v[52:53], v[6:7]
	v_pk_mul_f32 v[50:51], v[50:51], v[4:5]
	v_pk_mul_f32 v[48:49], v[48:49], v[178:179]
	v_pk_mul_f32 v[46:47], v[46:47], v[16:17]
	v_pk_mul_f32 v[44:45], v[44:45], v[14:15]
	v_pk_mul_f32 v[42:43], v[42:43], v[12:13]
	v_pk_mul_f32 v[40:41], v[40:41], v[10:11]
	v_pk_mul_f32 v[38:39], v[38:39], v[8:9]
	v_pk_mul_f32 v[36:37], v[36:37], v[6:7]
	v_pk_mul_f32 v[34:35], v[34:35], v[4:5]
	v_pk_mul_f32 v[32:33], v[32:33], v[178:179]
	v_pk_mul_f32 v[30:31], v[30:31], v[16:17]
	v_pk_mul_f32 v[28:29], v[28:29], v[14:15]
	v_pk_mul_f32 v[26:27], v[26:27], v[12:13]
	v_pk_mul_f32 v[24:25], v[24:25], v[10:11]
	v_pk_mul_f32 v[22:23], v[22:23], v[8:9]
	v_pk_mul_f32 v[20:21], v[20:21], v[6:7]
	v_pk_mul_f32 v[18:19], v[18:19], v[4:5]
	v_mul_f32_e32 v250, v250, v181
	v_mov_b32_e32 v251, v180

.Lat_farqk:
	s_and_b32 s22, s21, 0x8000
	s_add_i32 s8, s43, s22
	v_add_u32_e32 v16, s8, v246
	ds_read_b128 v[4:7], v16
	v_xor_b32_e32 v17, 32, v16
	ds_read_b128 v[12:15], v17
	v_xor_b32_e32 v190, 64, v16
	ds_read_b128 v[182:185], v190
	v_xor_b32_e32 v191, 0x60, v16
	ds_read_b128 v[8:11], v16 offset:8192
	ds_read_b128 v[178:181], v17 offset:8192
	ds_read_b128 v[186:189], v190 offset:8192
	s_waitcnt lgkmcnt(5)
	v_mfma_f32_32x32x16_bf16 v[162:177], v[4:7], v[210:213], 0
	ds_read_b128 v[4:7], v191
	s_waitcnt lgkmcnt(5)
	v_mfma_f32_32x32x16_bf16 v[162:177], v[12:15], v[214:217], v[162:177]
	ds_read_b128 v[12:15], v16 offset:128
	s_waitcnt lgkmcnt(5)
	v_mfma_f32_32x32x16_bf16 v[162:177], v[182:185], v[218:221], v[162:177]
	ds_read_b128 v[182:185], v17 offset:128
	s_waitcnt lgkmcnt(2)
	v_mfma_f32_32x32x16_bf16 v[162:177], v[4:7], v[222:225], v[162:177]
	ds_read_b128 v[4:7], v190 offset:128
	s_waitcnt lgkmcnt(2)
	v_mfma_f32_32x32x16_bf16 v[162:177], v[12:15], v[226:229], v[162:177]
	ds_read_b128 v[12:15], v191 offset:128
	s_waitcnt lgkmcnt(2)
	v_mfma_f32_32x32x16_bf16 v[162:177], v[182:185], v[230:233], v[162:177]
	s_waitcnt lgkmcnt(1)
	v_mfma_f32_32x32x16_bf16 v[162:177], v[4:7], v[234:237], v[162:177]
	s_waitcnt lgkmcnt(0)
	v_mfma_f32_32x32x16_bf16 v[162:177], v[12:15], v[238:241], v[162:177]
	v_mfma_f32_32x32x16_bf16 v[146:161], v[8:11], v[210:213], 0
	ds_read_b128 v[8:11], v191 offset:8192
	v_mfma_f32_32x32x16_bf16 v[146:161], v[178:181], v[214:217], v[146:161]
	ds_read_b128 v[178:181], v16 offset:8320
	v_sub_f32_e32 v4, v253, v251
	s_mov_b32 s8, 0x3e0293ee
	v_pk_fma_f32 v[194:195], v[162:163], s[8:9], v[4:5] op_sel_hi:[1,0,0]
	v_exp_f32_e32 v194, v194
	v_exp_f32_e32 v195, v195
	v_mfma_f32_32x32x16_bf16 v[146:161], v[186:189], v[218:221], v[146:161]
	ds_read_b128 v[186:189], v17 offset:8320
	v_pk_fma_f32 v[196:197], v[164:165], s[8:9], v[4:5] op_sel_hi:[1,0,0]
	v_exp_f32_e32 v196, v196
	v_exp_f32_e32 v197, v197
	s_waitcnt lgkmcnt(2)
	v_mfma_f32_32x32x16_bf16 v[146:161], v[8:11], v[222:225], v[146:161]
	ds_read_b128 v[8:11], v190 offset:8320
	v_pk_fma_f32 v[198:199], v[166:167], s[8:9], v[4:5] op_sel_hi:[1,0,0]
	v_exp_f32_e32 v198, v198
	v_exp_f32_e32 v199, v199
	v_pk_add_f32 v[6:7], v[194:195], v[196:197]
	s_waitcnt lgkmcnt(2)
	v_mfma_f32_32x32x16_bf16 v[146:161], v[178:181], v[226:229], v[146:161]
	ds_read_b128 v[178:181], v191 offset:8320
	v_pk_fma_f32 v[200:201], v[168:169], s[8:9], v[4:5] op_sel_hi:[1,0,0]
	v_exp_f32_e32 v200, v200
	v_exp_f32_e32 v201, v201
	v_pk_add_f32 v[6:7], v[6:7], v[198:199]
	s_waitcnt lgkmcnt(2)
	v_mfma_f32_32x32x16_bf16 v[146:161], v[186:189], v[230:233], v[146:161]
	v_pk_fma_f32 v[202:203], v[170:171], s[8:9], v[4:5] op_sel_hi:[1,0,0]
	v_exp_f32_e32 v202, v202
	v_exp_f32_e32 v203, v203
	v_pk_add_f32 v[6:7], v[6:7], v[200:201]
	s_waitcnt lgkmcnt(1)
	v_mfma_f32_32x32x16_bf16 v[146:161], v[8:11], v[234:237], v[146:161]
	v_pk_fma_f32 v[204:205], v[172:173], s[8:9], v[4:5] op_sel_hi:[1,0,0]
	v_exp_f32_e32 v204, v204
	v_exp_f32_e32 v205, v205
	v_pk_add_f32 v[6:7], v[6:7], v[202:203]
	s_waitcnt lgkmcnt(0)
	v_mfma_f32_32x32x16_bf16 v[146:161], v[178:181], v[238:241], v[146:161]
	v_pk_fma_f32 v[206:207], v[174:175], s[8:9], v[4:5] op_sel_hi:[1,0,0]
	v_exp_f32_e32 v206, v206
	v_exp_f32_e32 v207, v207
	v_pk_add_f32 v[6:7], v[6:7], v[204:205]
	v_pk_fma_f32 v[208:209], v[176:177], s[8:9], v[4:5] op_sel_hi:[1,0,0]
	v_exp_f32_e32 v208, v208
	v_exp_f32_e32 v209, v209
	v_pk_add_f32 v[6:7], v[6:7], v[206:207]
	v_max3_f32 v4, v162, v163, v164
	v_max3_f32 v4, v4, v165, v166
	v_max3_f32 v4, v4, v167, v168
	v_max3_f32 v4, v4, v169, v170
	v_max3_f32 v4, v4, v171, v172
	v_max3_f32 v4, v4, v173, v174
	v_max3_f32 v4, v4, v175, v176
	v_max3_f32 v4, v4, v177, v146
	v_max3_f32 v4, v4, v147, v148
	v_max3_f32 v4, v4, v149, v150
	v_max3_f32 v4, v4, v151, v152
	v_max3_f32 v4, v4, v153, v154
	v_max3_f32 v4, v4, v155, v156
	v_max3_f32 v4, v4, v157, v158
	v_max3_f32 v4, v4, v159, v160
	v_max_f32_e32 v4, v4, v161
	v_fmamk_f32 v4, v4, 0x3e0293ee, v253
	v_mov_b32_e32 v5, v4
	s_mov_b32 s8, 0x40c00000
	s_nop 0
	v_permlane32_swap_b32_e32 v5, v4
	v_max_f32_e32 v4, v4, v5
	v_sub_f32_e32 v5, v4, v251
	v_cmp_lt_f32_e32 vcc, s8, v5
	s_cbranch_vccnz .Lat_rescale
	v_sub_f32_e32 v4, v253, v251
	s_mov_b32 s8, 0x3e0293ee
	v_pk_fma_f32 v[178:179], v[146:147], s[8:9], v[4:5] op_sel_hi:[1,0,0]
	v_exp_f32_e32 v178, v178
	v_exp_f32_e32 v179, v179
	v_pk_fma_f32 v[180:181], v[148:149], s[8:9], v[4:5] op_sel_hi:[1,0,0]
	v_pk_add_f32 v[6:7], v[6:7], v[178:179]
	v_exp_f32_e32 v180, v180
	v_exp_f32_e32 v181, v181
	v_pk_fma_f32 v[182:183], v[150:151], s[8:9], v[4:5] op_sel_hi:[1,0,0]
	v_pk_add_f32 v[6:7], v[6:7], v[180:181]
	v_exp_f32_e32 v182, v182
	v_exp_f32_e32 v183, v183
	v_pk_fma_f32 v[184:185], v[152:153], s[8:9], v[4:5] op_sel_hi:[1,0,0]
	v_pk_add_f32 v[6:7], v[6:7], v[182:183]
	v_exp_f32_e32 v184, v184
	v_exp_f32_e32 v185, v185
	v_pk_fma_f32 v[186:187], v[154:155], s[8:9], v[4:5] op_sel_hi:[1,0,0]
	v_pk_add_f32 v[6:7], v[6:7], v[184:185]
	v_exp_f32_e32 v186, v186
	v_exp_f32_e32 v187, v187
	v_pk_fma_f32 v[188:189], v[156:157], s[8:9], v[4:5] op_sel_hi:[1,0,0]
	v_pk_add_f32 v[6:7], v[6:7], v[186:187]
	v_exp_f32_e32 v188, v188
	v_exp_f32_e32 v189, v189
	v_pk_fma_f32 v[190:191], v[158:159], s[8:9], v[4:5] op_sel_hi:[1,0,0]
	v_pk_add_f32 v[6:7], v[6:7], v[188:189]
	v_exp_f32_e32 v190, v190
	v_exp_f32_e32 v191, v191
	v_fmamk_f32 v2, v160, 0x3e0293ee, v4
	v_pk_add_f32 v[6:7], v[6:7], v[190:191]
	v_exp_f32_e32 v192, v2
	v_fmac_f32_e32 v4, 0x3e0293ee, v161
	v_add_f32_e32 v7, v6, v7
	v_add_f32_e32 v7, v7, v208
	v_add_f32_e32 v7, v7, v192
	s_add_i32 s19, s19, 1
	s_branch .LBB0_2759
